# prologue rmsnorm loop rewrite + bpermute->permlane swap in GEMM epilogues, mixer D code kept at its previous 32B alignment
# speedup vs baseline: 1.0089x; 1.0004x over previous
; DI unsigned cvtpk(float lo, float hi) { f32x2_t v = {lo, hi}; bf16x2_t b = __builtin_convertvector(v, bf16x2_t); return __builtin_bit_cast(unsigned, b); }
; DI float wave_sum(float v) {
; #pragma unroll
;   for (int o = 1; o < 64; o <<= 1) v += __shfl_xor(v, o);
;   return v;
; }
; DI void phase_prologue(const Params& p, char* lds) {
;     ...
;   { const float* x = p.in[I_X]; const float* g = p.in[I_NORM_GAIN]; bf16* H = (bf16*)(ws + WS_ACT);
;     const int gw = bid * 8 + wid, ngw = nb * 8;
;     for (int m = gw; m < NTOK; m += ngw) {
;       const f32x4* xr = (const f32x4*)(x + (size_t)m * DM) + lane;
;       f32x4 v[4]; float s = 0.f;
; #pragma unroll
;       for (int j = 0; j < 4; ++j) { v[j] = xr[64 * j]; s += v[j].x * v[j].x + v[j].y * v[j].y + v[j].z * v[j].z + v[j].w * v[j].w; }
;       const float rstd = rsqrtf(wave_sum(s) * (1.f / DM) + EPS);
;       u32x2* o = (u32x2*)(H + (size_t)m * DM) + lane;
; #pragma unroll
;       for (int j = 0; j < 4; ++j) { const f32x4 gg = *((const f32x4*)g + lane + 64 * j); u32x2 w; w.x = cvtpk(v[j].x * rstd * gg.x, v[j].y * rstd * gg.y); w.y = cvtpk(v[j].z * rstd * gg.z, v[j].w * rstd * gg.w); o[64 * j] = w; }
;     } }
.LBB0_113:
	s_or_b64 exec, exec, s[0:1]
	s_lshl_b32 s0, s25, 3
	v_writelane_b32 v254, s0, 13
	v_ashrrev_i32_e32 v1, 6, v1
	v_readlane_b32 s2, v254, 3
	v_readlane_b32 s3, v254, 4
	v_add_u32_e32 v4, s0, v1
	s_load_dwordx2 s[0:1], s[2:3], 0x158
	s_waitcnt lgkmcnt(0)
	s_lshl_b32 s10, s0, 3
	s_movk_i32 s0, 0x4000
	v_cmp_gt_i32_e32 vcc, s0, v4
	s_and_saveexec_b64 s[0:1], vcc
	s_cbranch_execz .LBB0_116
	v_mbcnt_hi_u32_b32 v5, -1, v135
	v_and_b32_e32 v1, 64, v5
	v_add_u32_e32 v6, 64, v1
	v_xor_b32_e32 v1, 1, v5
	v_cmp_lt_i32_e32 vcc, v1, v6
	v_xor_b32_e32 v7, 2, v5
	v_readlane_b32 s2, v254, 3
	v_cndmask_b32_e32 v1, v5, v1, vcc
	v_cmp_lt_i32_e32 vcc, v7, v6
	v_readlane_b32 s3, v254, 4
	s_load_dwordx2 s[4:5], s[2:3], 0x0
	s_nop 0
	s_load_dwordx2 s[2:3], s[2:3], 0x10
	v_cndmask_b32_e32 v7, v5, v7, vcc
	v_lshlrev_b32_e32 v10, 2, v7
	v_xor_b32_e32 v7, 4, v5
	v_cmp_lt_i32_e32 vcc, v7, v6
	v_lshlrev_b32_e32 v16, 4, v8
	v_mov_b32_e32 v17, 0
	v_cndmask_b32_e32 v7, v5, v7, vcc
	v_lshlrev_b32_e32 v11, 2, v7
	v_xor_b32_e32 v7, 8, v5
	v_cmp_lt_i32_e32 vcc, v7, v6
	s_ashr_i32 s11, s10, 31
	v_lshlrev_b32_e32 v1, 2, v1
	v_cndmask_b32_e32 v7, v5, v7, vcc
	v_lshlrev_b32_e32 v12, 2, v7
	v_xor_b32_e32 v7, 16, v5
	v_cmp_lt_i32_e32 vcc, v7, v6
	s_mov_b64 s[6:7], 0
	s_mov_b32 s8, 0x800000
	v_cndmask_b32_e32 v7, v5, v7, vcc
	v_lshlrev_b32_e32 v13, 2, v7
	v_xor_b32_e32 v7, 32, v5
	v_cmp_lt_i32_e32 vcc, v7, v6
	s_movk_i32 s9, 0x3fff
	s_nop 0
	v_cndmask_b32_e32 v5, v5, v7, vcc
	v_lshlrev_b32_e32 v14, 2, v5
	v_ashrrev_i32_e32 v5, 31, v4
	v_lshlrev_b64 v[18:19], 11, v[4:5]
	v_lshl_or_b32 v18, v8, 3, v18
	v_lshlrev_b64 v[8:9], 12, v[4:5]
	v_or_b32_e32 v8, v8, v16
	s_waitcnt lgkmcnt(0)
	v_lshl_add_u64 v[6:7], s[2:3], 0, v[16:17]
	v_lshl_add_u64 v[2:3], v[2:3], 0, v[18:19]
	s_mov_b64 s[2:3], 0x8000000
	v_lshl_add_u64 v[8:9], s[4:5], 0, v[8:9]
	s_mov_b64 s[4:5], 0xc00
	v_lshl_add_u64 v[2:3], v[2:3], 0, s[2:3]
	s_lshl_b64 s[2:3], s[10:11], 11
	v_lshl_add_u64 v[8:9], v[8:9], 0, s[4:5]
	s_lshl_b64 s[4:5], s[10:11], 12
	v_mov_b32_e32 v5, 0x358637bd
	global_load_dwordx4 v[200:203], v[6:7], off
	global_load_dwordx4 v[204:207], v[6:7], off offset:1024
	global_load_dwordx4 v[208:211], v[6:7], off offset:2048
	global_load_dwordx4 v[212:215], v[6:7], off offset:3072
	global_load_dwordx4 v[216:219], v[8:9], off offset:-3072
	global_load_dwordx4 v[220:223], v[8:9], off offset:-2048
	global_load_dwordx4 v[224:227], v[8:9], off offset:-1024
	global_load_dwordx4 v[228:231], v[8:9], off
	v_lshl_add_u64 v[8:9], v[8:9], 0, s[4:5]
	s_waitcnt vmcnt(0)
.LBB0_115:
	v_mov_b64_e32 v[16:17], v[216:217]
	v_mov_b64_e32 v[18:19], v[218:219]
	v_mov_b64_e32 v[20:21], v[220:221]
	v_mov_b64_e32 v[22:23], v[222:223]
	v_mov_b64_e32 v[24:25], v[224:225]
	v_mov_b64_e32 v[26:27], v[226:227]
	v_mov_b64_e32 v[28:29], v[228:229]
	v_mov_b64_e32 v[30:31], v[230:231]
	v_add_u32_e32 v4, s10, v4
	v_cmp_lt_i32_e32 vcc, s9, v4
	s_or_b64 s[6:7], vcc, s[6:7]
	s_mov_b64 s[12:13], exec
	s_andn2_b64 exec, exec, s[6:7]
	global_load_dwordx4 v[216:219], v[8:9], off offset:-3072
	global_load_dwordx4 v[220:223], v[8:9], off offset:-2048
	global_load_dwordx4 v[224:227], v[8:9], off offset:-1024
	global_load_dwordx4 v[228:231], v[8:9], off
	s_mov_b64 exec, s[12:13]
	v_lshl_add_u64 v[8:9], v[8:9], 0, s[4:5]
	v_mov_b32_e32 v38, v17
	v_mov_b32_e32 v39, v21
	v_mov_b32_e32 v36, v16
	v_mov_b32_e32 v37, v20
	v_mov_b32_e32 v46, v25
	v_mov_b32_e32 v47, v29
	v_pk_mul_f32 v[38:39], v[38:39], v[38:39]
	v_mov_b32_e32 v40, v18
	v_mov_b32_e32 v41, v22
	v_mov_b32_e32 v44, v24
	v_mov_b32_e32 v45, v28
	v_pk_mul_f32 v[46:47], v[46:47], v[46:47]
	v_pk_fma_f32 v[36:37], v[36:37], v[36:37], v[38:39]
	v_mov_b32_e32 v42, v19
	v_mov_b32_e32 v43, v23
	v_mov_b32_e32 v48, v26
	v_mov_b32_e32 v49, v30
	v_pk_fma_f32 v[38:39], v[44:45], v[44:45], v[46:47]
	v_pk_fma_f32 v[36:37], v[40:41], v[40:41], v[36:37]
	v_mov_b32_e32 v50, v27
	v_mov_b32_e32 v51, v31
	v_pk_fma_f32 v[38:39], v[48:49], v[48:49], v[38:39]
	v_pk_fma_f32 v[36:37], v[42:43], v[42:43], v[36:37]
	v_pk_fma_f32 v[38:39], v[50:51], v[50:51], v[38:39]
	v_add_f32_e32 v15, v36, v37
	v_add_f32_e32 v15, v15, v38
	v_add_f32_e32 v15, v15, v39
	v_mov_b32_e32 v36, v15
	s_nop 1
	v_permlane32_swap_b32_e32 v15, v36
	v_add_f32_e32 v15, v15, v36
	v_mov_b32_e32 v36, v15
	s_nop 1
	v_permlane16_swap_b32_e32 v15, v36
	v_add_f32_e32 v15, v15, v36
	s_nop 1
	v_add_f32_dpp v15, v15, v15 row_ror:8 row_mask:0xf bank_mask:0xf
	s_nop 1
	v_add_f32_dpp v15, v15, v15 row_ror:4 row_mask:0xf bank_mask:0xf
	s_nop 1
	v_add_f32_dpp v15, v15, v15 row_ror:2 row_mask:0xf bank_mask:0xf
	s_nop 1
	v_add_f32_dpp v15, v15, v15 row_ror:1 row_mask:0xf bank_mask:0xf
	s_nop 1
	v_fmamk_f32 v15, v15, 0x3a800000, v5
	v_mul_f32_e32 v36, 0x4b800000, v15
	v_cmp_gt_f32_e32 vcc, s8, v15
	s_nop 1
	v_cndmask_b32_e32 v15, v15, v36, vcc
	v_rsq_f32_e32 v15, v15
	s_nop 0
	v_mul_f32_e32 v36, 0x45800000, v15
	v_cndmask_b32_e32 v36, v15, v36, vcc
	v_pk_mul_f32 v[16:17], v[16:17], v[36:37] op_sel_hi:[1,0]
	v_pk_mul_f32 v[18:19], v[18:19], v[36:37] op_sel_hi:[1,0]
	v_pk_mul_f32 v[16:17], v[200:201], v[16:17]
	v_pk_mul_f32 v[18:19], v[202:203], v[18:19]
	v_cvt_pk_bf16_f32 v40, v16, v17
	v_cvt_pk_bf16_f32 v41, v18, v19
	global_store_dwordx2 v[2:3], v[40:41], off
	v_pk_mul_f32 v[20:21], v[20:21], v[36:37] op_sel_hi:[1,0]
	v_pk_mul_f32 v[22:23], v[22:23], v[36:37] op_sel_hi:[1,0]
	v_pk_mul_f32 v[20:21], v[204:205], v[20:21]
	v_pk_mul_f32 v[22:23], v[206:207], v[22:23]
	v_cvt_pk_bf16_f32 v42, v20, v21
	v_cvt_pk_bf16_f32 v43, v22, v23
	global_store_dwordx2 v[2:3], v[42:43], off offset:512
	v_pk_mul_f32 v[24:25], v[24:25], v[36:37] op_sel_hi:[1,0]
	v_pk_mul_f32 v[26:27], v[26:27], v[36:37] op_sel_hi:[1,0]
	v_pk_mul_f32 v[24:25], v[208:209], v[24:25]
	v_pk_mul_f32 v[26:27], v[210:211], v[26:27]
	v_cvt_pk_bf16_f32 v44, v24, v25
	v_cvt_pk_bf16_f32 v45, v26, v27
	global_store_dwordx2 v[2:3], v[44:45], off offset:1024
	v_pk_mul_f32 v[28:29], v[28:29], v[36:37] op_sel_hi:[1,0]
	v_pk_mul_f32 v[30:31], v[30:31], v[36:37] op_sel_hi:[1,0]
	v_pk_mul_f32 v[28:29], v[212:213], v[28:29]
	v_pk_mul_f32 v[30:31], v[214:215], v[30:31]
	v_cvt_pk_bf16_f32 v46, v28, v29
	v_cvt_pk_bf16_f32 v47, v30, v31
	global_store_dwordx2 v[2:3], v[46:47], off offset:1536
	v_lshl_add_u64 v[2:3], v[2:3], 0, s[2:3]
	s_waitcnt vmcnt(4)
	s_andn2_b64 exec, exec, s[6:7]
	s_cbranch_execnz .LBB0_115

; DI unsigned cvtpk(float lo, float hi) { f32x2_t v = {lo, hi}; bf16x2_t b = __builtin_convertvector(v, bf16x2_t); return __builtin_bit_cast(unsigned, b); }
;   DI void operator()(const f32x4 (&acc)[2][2][4][2], const pg8::Unit& u, int wr, int wc, int fr, int fq) const {
;     ...
;         const int row = u.pm * 256 + ai * 128 + wr * 64 + m * 16 + fr; float rs = 0.f;
; #pragma unroll
;         for (int bj = 0; bj < 2; ++bj)
; #pragma unroll
;           for (int n = 0; n < 2; ++n) {
;             const int col = u.pn * 256 + bj * 128 + wc * 32 + n * 16 + fq * 4; const size_t off = (size_t)row * DM + col;
;             f32x4 xb;
;             if (xin16) { const u32x2 hw = *(const u32x2*)(xin16 + off); xb.x = __uint_as_float(hw.x << 16); xb.y = __uint_as_float(hw.x & 0xffff0000u); xb.z = __uint_as_float(hw.y << 16); xb.w = __uint_as_float(hw.y & 0xffff0000u); }
;             else xb = *(const f32x4*)(xin + off);
;             const f32x4 xn = xb + acc[ai][bj][m][n];
;             { u32x2 wx; wx.x = cvtpk(xn.x, xn.y); wx.y = cvtpk(xn.z, xn.w); *(u32x2*)(X1B + off) = wx; }
;             rs += xn.x * xn.x + xn.y * xn.y + xn.z * xn.z + xn.w * xn.w;
;           }
;         rs += __shfl_xor(rs, 16); rs += __shfl_xor(rs, 32);
;         if (fq == 0) atomicAdd(ss + row, rs);
.LBB0_2256:
	v_lshl_add_u32 v142, s0, 8, v144
	v_lshl_or_b32 v140, s2, 8, v146
	v_ashrrev_i32_e32 v143, 31, v142
	v_lshlrev_b64 v[154:155], 10, v[142:143]
	v_ashrrev_i32_e32 v141, 31, v140
	v_lshl_add_u64 v[156:157], v[154:155], 0, v[140:141]
	v_lshl_add_u64 v[158:159], v[156:157], 2, s[10:11]
	global_load_dwordx4 v[150:153], v[158:159], off
	v_lshl_add_u64 v[156:157], v[156:157], 1, s[14:15]
	s_waitcnt vmcnt(0)
	v_pk_add_f32 v[126:127], v[126:127], v[152:153]
	v_pk_add_f32 v[160:161], v[124:125], v[150:151]
	v_cvt_pk_bf16_f32 v125, v126, v127
	v_cvt_pk_bf16_f32 v124, v160, v161
	global_store_dwordx2 v[156:157], v[124:125], off
	global_load_dwordx4 v[150:153], v[158:159], off offset:64
	v_or_b32_e32 v124, 16, v140
	v_ashrrev_i32_e32 v125, 31, v124
	v_lshl_add_u64 v[156:157], v[154:155], 0, v[124:125]
	v_lshl_add_u64 v[156:157], v[156:157], 1, s[14:15]
	s_waitcnt vmcnt(0)
	v_pk_add_f32 v[122:123], v[122:123], v[152:153]
	v_pk_add_f32 v[162:163], v[120:121], v[150:151]
	v_cvt_pk_bf16_f32 v121, v122, v123
	v_cvt_pk_bf16_f32 v120, v162, v163
	global_store_dwordx2 v[156:157], v[120:121], off
	global_load_dwordx4 v[150:153], v[158:159], off offset:512
	v_or_b32_e32 v120, 0x80, v140
	v_ashrrev_i32_e32 v121, 31, v120
	v_lshl_add_u64 v[156:157], v[154:155], 0, v[120:121]
	v_lshl_add_u64 v[156:157], v[156:157], 1, s[14:15]
	s_waitcnt vmcnt(0)
	v_pk_add_f32 v[118:119], v[118:119], v[152:153]
	v_pk_add_f32 v[164:165], v[116:117], v[150:151]
	v_cvt_pk_bf16_f32 v117, v118, v119
	v_cvt_pk_bf16_f32 v116, v164, v165
	global_store_dwordx2 v[156:157], v[116:117], off
	global_load_dwordx4 v[150:153], v[158:159], off offset:576
	v_and_b32_e32 v117, 64, v183
	v_xor_b32_e32 v116, 16, v183
	v_add_u32_e32 v117, 64, v117
	v_xor_b32_e32 v156, 32, v183
	v_cmp_lt_i32_e32 vcc, v116, v117
	s_nop 1
	v_cndmask_b32_e32 v116, v183, v116, vcc
	v_cmp_lt_i32_e32 vcc, v156, v117
	v_lshlrev_b32_e32 v116, 2, v116
	s_nop 0
	v_cndmask_b32_e32 v117, v183, v156, vcc
	v_mul_f32_e32 v156, v161, v161
	v_fmac_f32_e32 v156, v160, v160
	v_fmac_f32_e32 v156, v126, v126
	v_mul_f32_e32 v126, v163, v163
	v_fmac_f32_e32 v126, v162, v162
	v_fmac_f32_e32 v126, v122, v122
	v_fmac_f32_e32 v126, v123, v123
	v_mul_f32_e32 v123, v165, v165
	v_fmac_f32_e32 v123, v164, v164
	v_fmac_f32_e32 v156, v127, v127
	v_fmac_f32_e32 v123, v118, v118
	v_add_f32_e32 v122, v156, v126
	v_fmac_f32_e32 v123, v119, v119
	v_add_f32_e32 v126, v122, v123
	v_lshlrev_b32_e32 v117, 2, v117
	s_waitcnt vmcnt(0)
	v_pk_add_f32 v[122:123], v[112:113], v[150:151]
	s_nop 0
	v_mul_f32_e32 v112, v123, v123
	v_pk_add_f32 v[118:119], v[114:115], v[152:153]
	v_fmac_f32_e32 v112, v122, v122
	v_fmac_f32_e32 v112, v118, v118
	v_fmac_f32_e32 v112, v119, v119
	v_add_f32_e32 v114, v126, v112
	v_mov_b32_e32 v115, v114
	s_nop 1
	v_permlane16_swap_b32_e32 v114, v115
	v_or_b32_e32 v112, 0x90, v140
	v_ashrrev_i32_e32 v113, 31, v112
	v_lshl_add_u64 v[126:127], v[154:155], 0, v[112:113]
	v_cvt_pk_bf16_f32 v122, v122, v123
	s_waitcnt lgkmcnt(0)
	v_add_f32_e32 v114, v114, v115
	ds_bpermute_b32 v115, v117, v114
	v_cvt_pk_bf16_f32 v123, v118, v119
	v_lshl_add_u64 v[118:119], v[126:127], 1, s[14:15]
	global_store_dwordx2 v[118:119], v[122:123], off
	s_and_saveexec_b64 s[0:1], s[6:7]
	s_cbranch_execz .LBB0_2258
	s_waitcnt lgkmcnt(0)
	v_add_f32_e32 v118, v114, v115
	v_lshl_add_u64 v[114:115], v[142:143], 2, s[16:17]
	global_atomic_add_f32 v[114:115], v118, off

;   DI void operator()(const f32x4 (&acc)[2][2][4][2], const pg8::Unit& u, int wr, int wc, int fr, int fq) const {
;     ...
;         const int row = u.pm * 256 + ai * 128 + wr * 64 + m * 16 + fr, pos = row & (SEQ - 1);
;         float sc = 1.f;
;         if (layer == 1) sc = rsqrtf(ss1[row] * (1.f / DM) + EPS);
;         f32x4 v1[2], v2[2];
; #pragma unroll
;         for (int n = 0; n < 2; ++n) { v1[n] = acc[ai][0][m][n] * sc; v2[n] = acc[ai][1][m][n] * sc; }
;         if (type == T_NR) {
;           float s = 0.f;
; #pragma unroll
;           for (int n = 0; n < 2; ++n) s += v1[n].x * v1[n].x + v1[n].y * v1[n].y + v1[n].z * v1[n].z + v1[n].w * v1[n].w + v2[n].x * v2[n].x + v2[n].y * v2[n].y + v2[n].z * v2[n].z + v2[n].w * v2[n].w;
;           s += __shfl_xor(s, 16); s += __shfl_xor(s, 32);
;           const float rn = rsqrtf(s * (1.f / 64.f) + EPS);
; #pragma unroll
;           for (int n = 0; n < 2; ++n) { const f32x4 g1 = *(const f32x4*)(gain + n * 16 + fq * 4), g2 = *(const f32x4*)(gain + 32 + n * 16 + fq * 4); v1[n] = v1[n] * rn * g1; v2[n] = v2[n] * rn * g2; }
;         }
.LBB0_2470:
	s_cmp_eq_u32 s11, 1
	s_cselect_b64 s[2:3], -1, 0
	s_lshl_b32 s37, s0, 8
	s_add_i32 s37, s37, s54
	v_or_b32_e32 v148, s37, v152
	v_ashrrev_i32_e32 v149, 31, v148
	v_lshl_add_u64 v[146:147], v[148:149], 2, s[34:35]
	global_load_dword v146, v[146:147], off
	s_cmp_lg_u32 s11, 1
	s_waitcnt vmcnt(0)
	v_fmamk_f32 v146, v146, 0x3a800000, v160
	v_mul_f32_e32 v147, 0x4b800000, v146
	v_cmp_gt_f32_e32 vcc, s59, v146
	s_nop 1
	v_cndmask_b32_e32 v146, v146, v147, vcc
	v_rsq_f32_e32 v150, v146
	v_lshl_add_u64 v[146:147], s[8:9], 0, v[132:133]
	v_mul_f32_e32 v151, 0x45800000, v150
	v_cndmask_b32_e32 v162, v150, v151, vcc
	v_pk_mul_f32 v[126:127], v[126:127], v[162:163] op_sel_hi:[1,0]
	v_pk_mul_f32 v[124:125], v[124:125], v[162:163] op_sel_hi:[1,0]
	v_pk_mul_f32 v[118:119], v[118:119], v[162:163] op_sel_hi:[1,0]
	v_pk_mul_f32 v[116:117], v[116:117], v[162:163] op_sel_hi:[1,0]
	v_pk_mul_f32 v[150:151], v[122:123], v[162:163] op_sel_hi:[1,0]
	v_pk_mul_f32 v[120:121], v[120:121], v[162:163] op_sel_hi:[1,0]
	v_pk_mul_f32 v[122:123], v[114:115], v[162:163] op_sel_hi:[1,0]
	v_pk_mul_f32 v[114:115], v[112:113], v[162:163] op_sel_hi:[1,0]
	s_cbranch_scc1 .LBB0_2472
	global_load_dwordx4 v[162:165], v[146:147], off offset:64
	global_load_dwordx4 v[166:169], v[146:147], off
	global_load_dwordx4 v[170:173], v[146:147], off offset:192
	global_load_dwordx4 v[174:177], v[146:147], off offset:128
	v_mov_b32_e32 v178, v125
	v_mov_b32_e32 v179, v121
	v_mov_b32_e32 v112, v124
	v_mov_b32_e32 v113, v120
	v_pk_mul_f32 v[178:179], v[178:179], v[178:179]
	v_mov_b32_e32 v180, v126
	v_mov_b32_e32 v181, v150
	v_pk_fma_f32 v[112:113], v[112:113], v[112:113], v[178:179]
	v_mov_b32_e32 v184, v127
	v_mov_b32_e32 v185, v151
	v_pk_fma_f32 v[112:113], v[180:181], v[180:181], v[112:113]
	v_mov_b32_e32 v186, v116
	v_mov_b32_e32 v187, v114
	v_pk_fma_f32 v[112:113], v[184:185], v[184:185], v[112:113]
	v_mov_b32_e32 v188, v117
	v_mov_b32_e32 v189, v115
	v_and_b32_e32 v194, 64, v183
	v_pk_fma_f32 v[112:113], v[186:187], v[186:187], v[112:113]
	v_mov_b32_e32 v190, v118
	v_mov_b32_e32 v191, v122
	v_xor_b32_e32 v161, 16, v183
	v_add_u32_e32 v194, 64, v194
	v_pk_fma_f32 v[112:113], v[188:189], v[188:189], v[112:113]
	v_mov_b32_e32 v192, v119
	v_mov_b32_e32 v193, v123
	v_cmp_lt_i32_e32 vcc, v161, v194
	v_pk_fma_f32 v[112:113], v[190:191], v[190:191], v[112:113]
	s_nop 0
	v_cndmask_b32_e32 v161, v183, v161, vcc
	v_pk_fma_f32 v[112:113], v[192:193], v[192:193], v[112:113]
	v_lshlrev_b32_e32 v161, 2, v161
	v_add_f32_e32 v112, v112, v113
	v_mov_b32_e32 v113, v112
	s_nop 1
	v_permlane16_swap_b32_e32 v112, v113
	v_xor_b32_e32 v161, 32, v183
	v_cmp_lt_i32_e32 vcc, v161, v194
	s_waitcnt lgkmcnt(0)
	v_add_f32_e32 v112, v112, v113
	v_cndmask_b32_e32 v161, v183, v161, vcc
	v_lshlrev_b32_e32 v161, 2, v161
	v_mov_b32_e32 v113, v112
	s_nop 1
	v_permlane32_swap_b32_e32 v112, v113
	s_waitcnt lgkmcnt(0)
	v_add_f32_e32 v112, v112, v113
	v_fmamk_f32 v112, v112, 0x3c800000, v160
	v_mul_f32_e32 v113, 0x4b800000, v112
	v_cmp_gt_f32_e32 vcc, s59, v112
	s_nop 1
	v_cndmask_b32_e32 v112, v112, v113, vcc
	v_rsq_f32_e32 v112, v112
	s_nop 0
	v_mul_f32_e32 v113, 0x45800000, v112
	v_cndmask_b32_e32 v112, v112, v113, vcc
	v_pk_mul_f32 v[124:125], v[124:125], v[112:113] op_sel_hi:[1,0]
	v_pk_mul_f32 v[126:127], v[126:127], v[112:113] op_sel_hi:[1,0]
	v_pk_mul_f32 v[120:121], v[120:121], v[112:113] op_sel_hi:[1,0]
	v_pk_mul_f32 v[150:151], v[150:151], v[112:113] op_sel_hi:[1,0]
	v_pk_mul_f32 v[116:117], v[116:117], v[112:113] op_sel_hi:[1,0]
	v_pk_mul_f32 v[118:119], v[118:119], v[112:113] op_sel_hi:[1,0]
	v_pk_mul_f32 v[114:115], v[114:115], v[112:113] op_sel_hi:[1,0]
	v_pk_mul_f32 v[112:113], v[122:123], v[112:113] op_sel_hi:[1,0]
	s_waitcnt vmcnt(3)
	v_pk_mul_f32 v[150:151], v[164:165], v[150:151]
	v_pk_mul_f32 v[120:121], v[162:163], v[120:121]
	s_waitcnt vmcnt(2)
	v_pk_mul_f32 v[126:127], v[168:169], v[126:127]
	v_pk_mul_f32 v[124:125], v[166:167], v[124:125]
	s_waitcnt vmcnt(1)
	v_pk_mul_f32 v[122:123], v[172:173], v[112:113]
	v_pk_mul_f32 v[114:115], v[170:171], v[114:115]
	s_waitcnt vmcnt(0)
	v_pk_mul_f32 v[118:119], v[176:177], v[118:119]
	v_pk_mul_f32 v[116:117], v[174:175], v[116:117]

;   DI void operator()(const f32x4 (&acc)[2][2][4][2], const pg8::Unit& u, int wr, int wc, int fr, int fq) const {
;     ...
;         if (type == T_NR) {
;           float s = 0.f;
; #pragma unroll
;           for (int n = 0; n < 2; ++n) s += v1[n].x * v1[n].x + v1[n].y * v1[n].y + v1[n].z * v1[n].z + v1[n].w * v1[n].w + v2[n].x * v2[n].x + v2[n].y * v2[n].y + v2[n].z * v2[n].z + v2[n].w * v2[n].w;
;           s += __shfl_xor(s, 16); s += __shfl_xor(s, 32);
;           const float rn = rsqrtf(s * (1.f / 64.f) + EPS);
; #pragma unroll
;           for (int n = 0; n < 2; ++n) { const f32x4 g1 = *(const f32x4*)(gain + n * 16 + fq * 4), g2 = *(const f32x4*)(gain + 32 + n * 16 + fq * 4); v1[n] = v1[n] * rn * g1; v2[n] = v2[n] * rn * g2; }
;         }
.LBB0_2507:
	global_load_dwordx4 v[118:121], v[146:147], off offset:64
	global_load_dwordx4 v[122:125], v[146:147], off
	global_load_dwordx4 v[148:151], v[146:147], off offset:192
	global_load_dwordx4 v[162:165], v[146:147], off offset:128
	v_mov_b32_e32 v126, v117
	v_mov_b32_e32 v127, v101
	v_mov_b32_e32 v104, v116
	v_mov_b32_e32 v105, v100
	v_pk_mul_f32 v[126:127], v[126:127], v[126:127]
	v_mov_b32_e32 v166, v110
	v_mov_b32_e32 v167, v106
	v_pk_fma_f32 v[104:105], v[104:105], v[104:105], v[126:127]
	v_mov_b32_e32 v168, v111
	v_mov_b32_e32 v169, v107
	v_pk_fma_f32 v[104:105], v[166:167], v[166:167], v[104:105]
	v_mov_b32_e32 v170, v108
	v_mov_b32_e32 v171, v96
	v_pk_fma_f32 v[104:105], v[168:169], v[168:169], v[104:105]
	v_mov_b32_e32 v172, v109
	v_mov_b32_e32 v173, v97
	v_and_b32_e32 v178, 64, v183
	v_pk_fma_f32 v[104:105], v[170:171], v[170:171], v[104:105]
	v_mov_b32_e32 v174, v102
	v_mov_b32_e32 v175, v98
	v_xor_b32_e32 v161, 16, v183
	v_add_u32_e32 v178, 64, v178
	v_pk_fma_f32 v[104:105], v[172:173], v[172:173], v[104:105]
	v_mov_b32_e32 v176, v103
	v_mov_b32_e32 v177, v99
	v_cmp_lt_i32_e32 vcc, v161, v178
	v_pk_fma_f32 v[104:105], v[174:175], v[174:175], v[104:105]
	s_nop 0
	v_cndmask_b32_e32 v126, v183, v161, vcc
	v_pk_fma_f32 v[104:105], v[176:177], v[176:177], v[104:105]
	v_lshlrev_b32_e32 v126, 2, v126
	v_add_f32_e32 v104, v104, v105
	ds_bpermute_b32 v105, v126, v104
	v_xor_b32_e32 v126, 32, v183
	v_cmp_lt_i32_e32 vcc, v126, v178
	s_waitcnt lgkmcnt(0)
	v_add_f32_e32 v104, v104, v105
	v_cndmask_b32_e32 v126, v183, v126, vcc
	v_lshlrev_b32_e32 v126, 2, v126
	v_mov_b32_e32 v105, v104
	s_nop 1
	v_permlane32_swap_b32_e32 v104, v105
	s_waitcnt lgkmcnt(0)
	v_add_f32_e32 v104, v104, v105
	v_fmamk_f32 v104, v104, 0x3c800000, v160
	v_mul_f32_e32 v105, 0x4b800000, v104
	v_cmp_gt_f32_e32 vcc, s59, v104
	s_nop 1
	v_cndmask_b32_e32 v104, v104, v105, vcc
	v_rsq_f32_e32 v104, v104
	s_nop 0
	v_mul_f32_e32 v105, 0x45800000, v104
	v_cndmask_b32_e32 v104, v104, v105, vcc
	v_pk_mul_f32 v[116:117], v[116:117], v[104:105] op_sel_hi:[1,0]
	v_pk_mul_f32 v[110:111], v[110:111], v[104:105] op_sel_hi:[1,0]
	v_pk_mul_f32 v[100:101], v[100:101], v[104:105] op_sel_hi:[1,0]
	v_pk_mul_f32 v[106:107], v[106:107], v[104:105] op_sel_hi:[1,0]
	v_pk_mul_f32 v[108:109], v[108:109], v[104:105] op_sel_hi:[1,0]
	v_pk_mul_f32 v[102:103], v[102:103], v[104:105] op_sel_hi:[1,0]
	v_pk_mul_f32 v[96:97], v[96:97], v[104:105] op_sel_hi:[1,0]
	v_pk_mul_f32 v[98:99], v[98:99], v[104:105] op_sel_hi:[1,0]
	s_waitcnt vmcnt(3)
	v_pk_mul_f32 v[106:107], v[120:121], v[106:107]
	v_pk_mul_f32 v[100:101], v[118:119], v[100:101]
	s_waitcnt vmcnt(2)
	v_pk_mul_f32 v[110:111], v[124:125], v[110:111]
	v_pk_mul_f32 v[116:117], v[122:123], v[116:117]
	s_waitcnt vmcnt(1)
	v_pk_mul_f32 v[98:99], v[150:151], v[98:99]
	v_pk_mul_f32 v[96:97], v[148:149], v[96:97]
	s_waitcnt vmcnt(0)
	v_pk_mul_f32 v[102:103], v[164:165], v[102:103]
	v_pk_mul_f32 v[108:109], v[162:163], v[108:109]
	v_cndmask_b32_e64 v104, 0, 1, s[0:1]
	v_cmp_ne_u32_e64 s[10:11], 1, v104
	s_andn2_b64 vcc, exec, s[0:1]
	s_cbranch_vccnz .LBB0_2478

;   DI void operator()(const f32x4 (&acc)[2][2][4][2], const pg8::Unit& u, int wr, int wc, int fr, int fq) const {
;     ...
;         if (type == T_NR) {
;           float s = 0.f;
; #pragma unroll
;           for (int n = 0; n < 2; ++n) s += v1[n].x * v1[n].x + v1[n].y * v1[n].y + v1[n].z * v1[n].z + v1[n].w * v1[n].w + v2[n].x * v2[n].x + v2[n].y * v2[n].y + v2[n].z * v2[n].z + v2[n].w * v2[n].w;
;           s += __shfl_xor(s, 16); s += __shfl_xor(s, 32);
;           const float rn = rsqrtf(s * (1.f / 64.f) + EPS);
; #pragma unroll
;           for (int n = 0; n < 2; ++n) { const f32x4 g1 = *(const f32x4*)(gain + n * 16 + fq * 4), g2 = *(const f32x4*)(gain + 32 + n * 16 + fq * 4); v1[n] = v1[n] * rn * g1; v2[n] = v2[n] * rn * g2; }
;         }
.LBB0_2509:
	global_load_dwordx4 v[100:103], v[146:147], off offset:64
	global_load_dwordx4 v[104:107], v[146:147], off
	global_load_dwordx4 v[108:111], v[146:147], off offset:192
	global_load_dwordx4 v[114:117], v[146:147], off offset:128
	v_mov_b32_e32 v118, v99
	v_mov_b32_e32 v119, v85
	v_mov_b32_e32 v88, v98
	v_mov_b32_e32 v89, v84
	v_pk_mul_f32 v[118:119], v[118:119], v[118:119]
	v_mov_b32_e32 v120, v94
	v_mov_b32_e32 v121, v90
	v_pk_fma_f32 v[88:89], v[88:89], v[88:89], v[118:119]
	v_mov_b32_e32 v122, v95
	v_mov_b32_e32 v123, v91
	v_pk_fma_f32 v[88:89], v[120:121], v[120:121], v[88:89]
	v_mov_b32_e32 v124, v92
	v_mov_b32_e32 v125, v80
	v_pk_fma_f32 v[88:89], v[122:123], v[122:123], v[88:89]
	v_mov_b32_e32 v126, v93
	v_mov_b32_e32 v127, v81
	v_and_b32_e32 v162, 64, v183
	v_pk_fma_f32 v[88:89], v[124:125], v[124:125], v[88:89]
	v_mov_b32_e32 v148, v86
	v_mov_b32_e32 v149, v82
	v_xor_b32_e32 v161, 16, v183
	v_add_u32_e32 v162, 64, v162
	v_pk_fma_f32 v[88:89], v[126:127], v[126:127], v[88:89]
	v_mov_b32_e32 v150, v87
	v_mov_b32_e32 v151, v83
	v_cmp_lt_i32_e32 vcc, v161, v162
	v_pk_fma_f32 v[88:89], v[148:149], v[148:149], v[88:89]
	s_nop 0
	v_cndmask_b32_e32 v118, v183, v161, vcc
	v_pk_fma_f32 v[88:89], v[150:151], v[150:151], v[88:89]
	v_lshlrev_b32_e32 v118, 2, v118
	v_add_f32_e32 v88, v88, v89
	ds_bpermute_b32 v89, v118, v88
	v_xor_b32_e32 v118, 32, v183
	v_cmp_lt_i32_e32 vcc, v118, v162
	s_waitcnt lgkmcnt(0)
	v_add_f32_e32 v88, v88, v89
	v_cndmask_b32_e32 v118, v183, v118, vcc
	v_lshlrev_b32_e32 v118, 2, v118
	v_mov_b32_e32 v89, v88
	s_nop 1
	v_permlane32_swap_b32_e32 v88, v89
	s_waitcnt lgkmcnt(0)
	v_add_f32_e32 v88, v88, v89
	v_fmamk_f32 v88, v88, 0x3c800000, v160
	v_mul_f32_e32 v89, 0x4b800000, v88
	v_cmp_gt_f32_e32 vcc, s59, v88
	s_nop 1
	v_cndmask_b32_e32 v88, v88, v89, vcc
	v_rsq_f32_e32 v88, v88
	s_nop 0
	v_mul_f32_e32 v89, 0x45800000, v88
	v_cndmask_b32_e32 v88, v88, v89, vcc
	v_pk_mul_f32 v[98:99], v[98:99], v[88:89] op_sel_hi:[1,0]
	v_pk_mul_f32 v[94:95], v[94:95], v[88:89] op_sel_hi:[1,0]
	v_pk_mul_f32 v[84:85], v[84:85], v[88:89] op_sel_hi:[1,0]
	v_pk_mul_f32 v[90:91], v[90:91], v[88:89] op_sel_hi:[1,0]
	v_pk_mul_f32 v[92:93], v[92:93], v[88:89] op_sel_hi:[1,0]
	v_pk_mul_f32 v[86:87], v[86:87], v[88:89] op_sel_hi:[1,0]
	v_pk_mul_f32 v[80:81], v[80:81], v[88:89] op_sel_hi:[1,0]
	v_pk_mul_f32 v[82:83], v[82:83], v[88:89] op_sel_hi:[1,0]
	s_waitcnt vmcnt(3)
	v_pk_mul_f32 v[90:91], v[102:103], v[90:91]
	v_pk_mul_f32 v[84:85], v[100:101], v[84:85]
	s_waitcnt vmcnt(2)
	v_pk_mul_f32 v[94:95], v[106:107], v[94:95]
	v_pk_mul_f32 v[98:99], v[104:105], v[98:99]
	s_waitcnt vmcnt(1)
	v_pk_mul_f32 v[82:83], v[110:111], v[82:83]
	v_pk_mul_f32 v[80:81], v[108:109], v[80:81]
	s_waitcnt vmcnt(0)
	v_pk_mul_f32 v[86:87], v[116:117], v[86:87]
	v_pk_mul_f32 v[92:93], v[114:115], v[92:93]
	s_and_b64 vcc, exec, s[10:11]
	s_cbranch_vccnz .LBB0_2482

;   DI void operator()(const f32x4 (&acc)[2][2][4][2], const pg8::Unit& u, int wr, int wc, int fr, int fq) const {
;     ...
;         if (type == T_NR) {
;           float s = 0.f;
; #pragma unroll
;           for (int n = 0; n < 2; ++n) s += v1[n].x * v1[n].x + v1[n].y * v1[n].y + v1[n].z * v1[n].z + v1[n].w * v1[n].w + v2[n].x * v2[n].x + v2[n].y * v2[n].y + v2[n].z * v2[n].z + v2[n].w * v2[n].w;
;           s += __shfl_xor(s, 16); s += __shfl_xor(s, 32);
;           const float rn = rsqrtf(s * (1.f / 64.f) + EPS);
; #pragma unroll
;           for (int n = 0; n < 2; ++n) { const f32x4 g1 = *(const f32x4*)(gain + n * 16 + fq * 4), g2 = *(const f32x4*)(gain + 32 + n * 16 + fq * 4); v1[n] = v1[n] * rn * g1; v2[n] = v2[n] * rn * g2; }
;         }
.LBB0_2511:
	global_load_dwordx4 v[84:87], v[146:147], off offset:64
	global_load_dwordx4 v[88:91], v[146:147], off
	global_load_dwordx4 v[92:95], v[146:147], off offset:192
	global_load_dwordx4 v[96:99], v[146:147], off offset:128
	v_mov_b32_e32 v100, v83
	v_mov_b32_e32 v101, v69
	v_mov_b32_e32 v72, v82
	v_mov_b32_e32 v73, v68
	v_pk_mul_f32 v[100:101], v[100:101], v[100:101]
	v_mov_b32_e32 v102, v78
	v_mov_b32_e32 v103, v74
	v_pk_fma_f32 v[72:73], v[72:73], v[72:73], v[100:101]
	v_mov_b32_e32 v104, v79
	v_mov_b32_e32 v105, v75
	v_pk_fma_f32 v[72:73], v[102:103], v[102:103], v[72:73]
	v_mov_b32_e32 v106, v76
	v_mov_b32_e32 v107, v64
	v_pk_fma_f32 v[72:73], v[104:105], v[104:105], v[72:73]
	v_mov_b32_e32 v108, v77
	v_mov_b32_e32 v109, v65
	v_and_b32_e32 v117, 64, v183
	v_pk_fma_f32 v[72:73], v[106:107], v[106:107], v[72:73]
	v_mov_b32_e32 v110, v70
	v_mov_b32_e32 v111, v66
	v_xor_b32_e32 v116, 16, v183
	v_add_u32_e32 v117, 64, v117
	v_pk_fma_f32 v[72:73], v[108:109], v[108:109], v[72:73]
	v_mov_b32_e32 v114, v71
	v_mov_b32_e32 v115, v67
	v_cmp_lt_i32_e32 vcc, v116, v117
	v_pk_fma_f32 v[72:73], v[110:111], v[110:111], v[72:73]
	s_nop 0
	v_cndmask_b32_e32 v100, v183, v116, vcc
	v_pk_fma_f32 v[72:73], v[114:115], v[114:115], v[72:73]
	v_lshlrev_b32_e32 v100, 2, v100
	v_add_f32_e32 v72, v72, v73
	ds_bpermute_b32 v73, v100, v72
	v_xor_b32_e32 v100, 32, v183
	v_cmp_lt_i32_e32 vcc, v100, v117
	s_waitcnt lgkmcnt(0)
	v_add_f32_e32 v72, v72, v73
	v_cndmask_b32_e32 v100, v183, v100, vcc
	v_lshlrev_b32_e32 v100, 2, v100
	v_mov_b32_e32 v73, v72
	s_nop 1
	v_permlane32_swap_b32_e32 v72, v73
	s_waitcnt lgkmcnt(0)
	v_add_f32_e32 v72, v72, v73
	v_fmamk_f32 v72, v72, 0x3c800000, v160
	v_mul_f32_e32 v73, 0x4b800000, v72
	v_cmp_gt_f32_e32 vcc, s59, v72
	s_nop 1
	v_cndmask_b32_e32 v72, v72, v73, vcc
	v_rsq_f32_e32 v72, v72
	s_nop 0
	v_mul_f32_e32 v73, 0x45800000, v72
	v_cndmask_b32_e32 v72, v72, v73, vcc
	v_pk_mul_f32 v[82:83], v[82:83], v[72:73] op_sel_hi:[1,0]
	v_pk_mul_f32 v[78:79], v[78:79], v[72:73] op_sel_hi:[1,0]
	v_pk_mul_f32 v[68:69], v[68:69], v[72:73] op_sel_hi:[1,0]
	v_pk_mul_f32 v[74:75], v[74:75], v[72:73] op_sel_hi:[1,0]
	v_pk_mul_f32 v[76:77], v[76:77], v[72:73] op_sel_hi:[1,0]
	v_pk_mul_f32 v[70:71], v[70:71], v[72:73] op_sel_hi:[1,0]
	v_pk_mul_f32 v[64:65], v[64:65], v[72:73] op_sel_hi:[1,0]
	v_pk_mul_f32 v[66:67], v[66:67], v[72:73] op_sel_hi:[1,0]
	s_waitcnt vmcnt(3)
	v_pk_mul_f32 v[74:75], v[86:87], v[74:75]
	v_pk_mul_f32 v[68:69], v[84:85], v[68:69]
	s_waitcnt vmcnt(2)
	v_pk_mul_f32 v[78:79], v[90:91], v[78:79]
	v_pk_mul_f32 v[82:83], v[88:89], v[82:83]
	s_waitcnt vmcnt(1)
	v_pk_mul_f32 v[66:67], v[94:95], v[66:67]
	v_pk_mul_f32 v[64:65], v[92:93], v[64:65]
	s_waitcnt vmcnt(0)
	v_pk_mul_f32 v[70:71], v[98:99], v[70:71]
	v_pk_mul_f32 v[76:77], v[96:97], v[76:77]
	s_and_b64 vcc, exec, s[10:11]
	s_cbranch_vccnz .LBB0_2486

;   DI void operator()(const f32x4 (&acc)[2][2][4][2], const pg8::Unit& u, int wr, int wc, int fr, int fq) const {
;     ...
;         if (type == T_NR) {
;           float s = 0.f;
; #pragma unroll
;           for (int n = 0; n < 2; ++n) s += v1[n].x * v1[n].x + v1[n].y * v1[n].y + v1[n].z * v1[n].z + v1[n].w * v1[n].w + v2[n].x * v2[n].x + v2[n].y * v2[n].y + v2[n].z * v2[n].z + v2[n].w * v2[n].w;
;           s += __shfl_xor(s, 16); s += __shfl_xor(s, 32);
;           const float rn = rsqrtf(s * (1.f / 64.f) + EPS);
; #pragma unroll
;           for (int n = 0; n < 2; ++n) { const f32x4 g1 = *(const f32x4*)(gain + n * 16 + fq * 4), g2 = *(const f32x4*)(gain + 32 + n * 16 + fq * 4); v1[n] = v1[n] * rn * g1; v2[n] = v2[n] * rn * g2; }
;         }
.LBB0_2513:
	global_load_dwordx4 v[68:71], v[146:147], off offset:64
	global_load_dwordx4 v[72:75], v[146:147], off
	global_load_dwordx4 v[76:79], v[146:147], off offset:192
	global_load_dwordx4 v[80:83], v[146:147], off offset:128
	v_mov_b32_e32 v84, v67
	v_mov_b32_e32 v85, v53
	v_mov_b32_e32 v56, v66
	v_mov_b32_e32 v57, v52
	v_pk_mul_f32 v[84:85], v[84:85], v[84:85]
	v_mov_b32_e32 v86, v62
	v_mov_b32_e32 v87, v58
	v_pk_fma_f32 v[56:57], v[56:57], v[56:57], v[84:85]
	v_mov_b32_e32 v88, v63
	v_mov_b32_e32 v89, v59
	v_pk_fma_f32 v[56:57], v[86:87], v[86:87], v[56:57]
	v_mov_b32_e32 v90, v60
	v_mov_b32_e32 v91, v48
	v_pk_fma_f32 v[56:57], v[88:89], v[88:89], v[56:57]
	v_mov_b32_e32 v92, v61
	v_mov_b32_e32 v93, v49
	v_and_b32_e32 v99, 64, v183
	v_pk_fma_f32 v[56:57], v[90:91], v[90:91], v[56:57]
	v_mov_b32_e32 v94, v54
	v_mov_b32_e32 v95, v50
	v_xor_b32_e32 v98, 16, v183
	v_add_u32_e32 v99, 64, v99
	v_pk_fma_f32 v[56:57], v[92:93], v[92:93], v[56:57]
	v_mov_b32_e32 v96, v55
	v_mov_b32_e32 v97, v51
	v_cmp_lt_i32_e32 vcc, v98, v99
	v_pk_fma_f32 v[56:57], v[94:95], v[94:95], v[56:57]
	s_nop 0
	v_cndmask_b32_e32 v84, v183, v98, vcc
	v_pk_fma_f32 v[56:57], v[96:97], v[96:97], v[56:57]
	v_lshlrev_b32_e32 v84, 2, v84
	v_add_f32_e32 v56, v56, v57
	ds_bpermute_b32 v57, v84, v56
	v_xor_b32_e32 v84, 32, v183
	v_cmp_lt_i32_e32 vcc, v84, v99
	s_waitcnt lgkmcnt(0)
	v_add_f32_e32 v56, v56, v57
	v_cndmask_b32_e32 v84, v183, v84, vcc
	v_lshlrev_b32_e32 v84, 2, v84
	v_mov_b32_e32 v57, v56
	s_nop 1
	v_permlane32_swap_b32_e32 v56, v57
	s_waitcnt lgkmcnt(0)
	v_add_f32_e32 v56, v56, v57
	v_fmamk_f32 v56, v56, 0x3c800000, v160
	v_mul_f32_e32 v57, 0x4b800000, v56
	v_cmp_gt_f32_e32 vcc, s59, v56
	s_nop 1
	v_cndmask_b32_e32 v56, v56, v57, vcc
	v_rsq_f32_e32 v56, v56
	s_nop 0
	v_mul_f32_e32 v57, 0x45800000, v56
	v_cndmask_b32_e32 v56, v56, v57, vcc
	v_pk_mul_f32 v[66:67], v[66:67], v[56:57] op_sel_hi:[1,0]
	v_pk_mul_f32 v[62:63], v[62:63], v[56:57] op_sel_hi:[1,0]
	v_pk_mul_f32 v[52:53], v[52:53], v[56:57] op_sel_hi:[1,0]
	v_pk_mul_f32 v[58:59], v[58:59], v[56:57] op_sel_hi:[1,0]
	v_pk_mul_f32 v[60:61], v[60:61], v[56:57] op_sel_hi:[1,0]
	v_pk_mul_f32 v[54:55], v[54:55], v[56:57] op_sel_hi:[1,0]
	v_pk_mul_f32 v[48:49], v[48:49], v[56:57] op_sel_hi:[1,0]
	v_pk_mul_f32 v[50:51], v[50:51], v[56:57] op_sel_hi:[1,0]
	s_waitcnt vmcnt(3)
	v_pk_mul_f32 v[58:59], v[70:71], v[58:59]
	v_pk_mul_f32 v[52:53], v[68:69], v[52:53]
	s_waitcnt vmcnt(2)
	v_pk_mul_f32 v[62:63], v[74:75], v[62:63]
	v_pk_mul_f32 v[66:67], v[72:73], v[66:67]
	s_waitcnt vmcnt(1)
	v_pk_mul_f32 v[50:51], v[78:79], v[50:51]
	v_pk_mul_f32 v[48:49], v[76:77], v[48:49]
	s_waitcnt vmcnt(0)
	v_pk_mul_f32 v[54:55], v[82:83], v[54:55]
	v_pk_mul_f32 v[60:61], v[80:81], v[60:61]
	s_and_b64 vcc, exec, s[10:11]
	s_cbranch_vccnz .LBB0_2490

;   DI void operator()(const f32x4 (&acc)[2][2][4][2], const pg8::Unit& u, int wr, int wc, int fr, int fq) const {
;     ...
;         if (type == T_NR) {
;           float s = 0.f;
; #pragma unroll
;           for (int n = 0; n < 2; ++n) s += v1[n].x * v1[n].x + v1[n].y * v1[n].y + v1[n].z * v1[n].z + v1[n].w * v1[n].w + v2[n].x * v2[n].x + v2[n].y * v2[n].y + v2[n].z * v2[n].z + v2[n].w * v2[n].w;
;           s += __shfl_xor(s, 16); s += __shfl_xor(s, 32);
;           const float rn = rsqrtf(s * (1.f / 64.f) + EPS);
; #pragma unroll
;           for (int n = 0; n < 2; ++n) { const f32x4 g1 = *(const f32x4*)(gain + n * 16 + fq * 4), g2 = *(const f32x4*)(gain + 32 + n * 16 + fq * 4); v1[n] = v1[n] * rn * g1; v2[n] = v2[n] * rn * g2; }
;         }
.LBB0_2515:
	global_load_dwordx4 v[52:55], v[146:147], off offset:64
	global_load_dwordx4 v[56:59], v[146:147], off
	global_load_dwordx4 v[60:63], v[146:147], off offset:192
	global_load_dwordx4 v[64:67], v[146:147], off offset:128
	v_mov_b32_e32 v68, v51
	v_mov_b32_e32 v69, v37
	v_mov_b32_e32 v40, v50
	v_mov_b32_e32 v41, v36
	v_pk_mul_f32 v[68:69], v[68:69], v[68:69]
	v_mov_b32_e32 v70, v46
	v_mov_b32_e32 v71, v42
	v_pk_fma_f32 v[40:41], v[40:41], v[40:41], v[68:69]
	v_mov_b32_e32 v72, v47
	v_mov_b32_e32 v73, v43
	v_pk_fma_f32 v[40:41], v[70:71], v[70:71], v[40:41]
	v_mov_b32_e32 v74, v44
	v_mov_b32_e32 v75, v32
	v_pk_fma_f32 v[40:41], v[72:73], v[72:73], v[40:41]
	v_mov_b32_e32 v76, v45
	v_mov_b32_e32 v77, v33
	v_and_b32_e32 v83, 64, v183
	v_pk_fma_f32 v[40:41], v[74:75], v[74:75], v[40:41]
	v_mov_b32_e32 v78, v38
	v_mov_b32_e32 v79, v34
	v_xor_b32_e32 v82, 16, v183
	v_add_u32_e32 v83, 64, v83
	v_pk_fma_f32 v[40:41], v[76:77], v[76:77], v[40:41]
	v_mov_b32_e32 v80, v39
	v_mov_b32_e32 v81, v35
	v_cmp_lt_i32_e32 vcc, v82, v83
	v_pk_fma_f32 v[40:41], v[78:79], v[78:79], v[40:41]
	s_nop 0
	v_cndmask_b32_e32 v68, v183, v82, vcc
	v_pk_fma_f32 v[40:41], v[80:81], v[80:81], v[40:41]
	v_lshlrev_b32_e32 v68, 2, v68
	v_add_f32_e32 v40, v40, v41
	ds_bpermute_b32 v41, v68, v40
	v_xor_b32_e32 v68, 32, v183
	v_cmp_lt_i32_e32 vcc, v68, v83
	s_waitcnt lgkmcnt(0)
	v_add_f32_e32 v40, v40, v41
	v_cndmask_b32_e32 v68, v183, v68, vcc
	v_lshlrev_b32_e32 v68, 2, v68
	v_mov_b32_e32 v41, v40
	s_nop 1
	v_permlane32_swap_b32_e32 v40, v41
	s_waitcnt lgkmcnt(0)
	v_add_f32_e32 v40, v40, v41
	v_fmamk_f32 v40, v40, 0x3c800000, v160
	v_mul_f32_e32 v41, 0x4b800000, v40
	v_cmp_gt_f32_e32 vcc, s59, v40
	s_nop 1
	v_cndmask_b32_e32 v40, v40, v41, vcc
	v_rsq_f32_e32 v40, v40
	s_nop 0
	v_mul_f32_e32 v41, 0x45800000, v40
	v_cndmask_b32_e32 v40, v40, v41, vcc
	v_pk_mul_f32 v[50:51], v[50:51], v[40:41] op_sel_hi:[1,0]
	v_pk_mul_f32 v[46:47], v[46:47], v[40:41] op_sel_hi:[1,0]
	v_pk_mul_f32 v[36:37], v[36:37], v[40:41] op_sel_hi:[1,0]
	v_pk_mul_f32 v[42:43], v[42:43], v[40:41] op_sel_hi:[1,0]
	v_pk_mul_f32 v[44:45], v[44:45], v[40:41] op_sel_hi:[1,0]
	v_pk_mul_f32 v[38:39], v[38:39], v[40:41] op_sel_hi:[1,0]
	v_pk_mul_f32 v[32:33], v[32:33], v[40:41] op_sel_hi:[1,0]
	v_pk_mul_f32 v[34:35], v[34:35], v[40:41] op_sel_hi:[1,0]
	s_waitcnt vmcnt(3)
	v_pk_mul_f32 v[42:43], v[54:55], v[42:43]
	v_pk_mul_f32 v[36:37], v[52:53], v[36:37]
	s_waitcnt vmcnt(2)
	v_pk_mul_f32 v[46:47], v[58:59], v[46:47]
	v_pk_mul_f32 v[50:51], v[56:57], v[50:51]
	s_waitcnt vmcnt(1)
	v_pk_mul_f32 v[34:35], v[62:63], v[34:35]
	v_pk_mul_f32 v[32:33], v[60:61], v[32:33]
	s_waitcnt vmcnt(0)
	v_pk_mul_f32 v[38:39], v[66:67], v[38:39]
	v_pk_mul_f32 v[44:45], v[64:65], v[44:45]
	s_and_b64 vcc, exec, s[10:11]
	s_cbranch_vccnz .LBB0_2494

;   DI void operator()(const f32x4 (&acc)[2][2][4][2], const pg8::Unit& u, int wr, int wc, int fr, int fq) const {
;     ...
;         if (type == T_NR) {
;           float s = 0.f;
; #pragma unroll
;           for (int n = 0; n < 2; ++n) s += v1[n].x * v1[n].x + v1[n].y * v1[n].y + v1[n].z * v1[n].z + v1[n].w * v1[n].w + v2[n].x * v2[n].x + v2[n].y * v2[n].y + v2[n].z * v2[n].z + v2[n].w * v2[n].w;
;           s += __shfl_xor(s, 16); s += __shfl_xor(s, 32);
;           const float rn = rsqrtf(s * (1.f / 64.f) + EPS);
; #pragma unroll
;           for (int n = 0; n < 2; ++n) { const f32x4 g1 = *(const f32x4*)(gain + n * 16 + fq * 4), g2 = *(const f32x4*)(gain + 32 + n * 16 + fq * 4); v1[n] = v1[n] * rn * g1; v2[n] = v2[n] * rn * g2; }
;         }
.LBB0_2517:
	global_load_dwordx4 v[36:39], v[146:147], off offset:64
	global_load_dwordx4 v[40:43], v[146:147], off
	global_load_dwordx4 v[44:47], v[146:147], off offset:192
	global_load_dwordx4 v[48:51], v[146:147], off offset:128
	v_mov_b32_e32 v52, v35
	v_mov_b32_e32 v53, v21
	v_mov_b32_e32 v24, v34
	v_mov_b32_e32 v25, v20
	v_pk_mul_f32 v[52:53], v[52:53], v[52:53]
	v_mov_b32_e32 v54, v30
	v_mov_b32_e32 v55, v26
	v_pk_fma_f32 v[24:25], v[24:25], v[24:25], v[52:53]
	v_mov_b32_e32 v56, v31
	v_mov_b32_e32 v57, v27
	v_pk_fma_f32 v[24:25], v[54:55], v[54:55], v[24:25]
	v_mov_b32_e32 v58, v28
	v_mov_b32_e32 v59, v16
	v_pk_fma_f32 v[24:25], v[56:57], v[56:57], v[24:25]
	v_mov_b32_e32 v60, v29
	v_mov_b32_e32 v61, v17
	v_and_b32_e32 v67, 64, v183
	v_pk_fma_f32 v[24:25], v[58:59], v[58:59], v[24:25]
	v_mov_b32_e32 v62, v22
	v_mov_b32_e32 v63, v18
	v_xor_b32_e32 v66, 16, v183
	v_add_u32_e32 v67, 64, v67
	v_pk_fma_f32 v[24:25], v[60:61], v[60:61], v[24:25]
	v_mov_b32_e32 v64, v23
	v_mov_b32_e32 v65, v19
	v_cmp_lt_i32_e32 vcc, v66, v67
	v_pk_fma_f32 v[24:25], v[62:63], v[62:63], v[24:25]
	s_nop 0
	v_cndmask_b32_e32 v52, v183, v66, vcc
	v_pk_fma_f32 v[24:25], v[64:65], v[64:65], v[24:25]
	v_lshlrev_b32_e32 v52, 2, v52
	v_add_f32_e32 v24, v24, v25
	ds_bpermute_b32 v25, v52, v24
	v_xor_b32_e32 v52, 32, v183
	v_cmp_lt_i32_e32 vcc, v52, v67
	s_waitcnt lgkmcnt(0)
	v_add_f32_e32 v24, v24, v25
	v_cndmask_b32_e32 v52, v183, v52, vcc
	v_lshlrev_b32_e32 v52, 2, v52
	v_mov_b32_e32 v25, v24
	s_nop 1
	v_permlane32_swap_b32_e32 v24, v25
	s_waitcnt lgkmcnt(0)
	v_add_f32_e32 v24, v24, v25
	v_fmamk_f32 v24, v24, 0x3c800000, v160
	v_mul_f32_e32 v25, 0x4b800000, v24
	v_cmp_gt_f32_e32 vcc, s59, v24
	s_nop 1
	v_cndmask_b32_e32 v24, v24, v25, vcc
	v_rsq_f32_e32 v24, v24
	s_nop 0
	v_mul_f32_e32 v25, 0x45800000, v24
	v_cndmask_b32_e32 v24, v24, v25, vcc
	v_pk_mul_f32 v[34:35], v[34:35], v[24:25] op_sel_hi:[1,0]
	v_pk_mul_f32 v[30:31], v[30:31], v[24:25] op_sel_hi:[1,0]
	v_pk_mul_f32 v[20:21], v[20:21], v[24:25] op_sel_hi:[1,0]
	v_pk_mul_f32 v[26:27], v[26:27], v[24:25] op_sel_hi:[1,0]
	v_pk_mul_f32 v[28:29], v[28:29], v[24:25] op_sel_hi:[1,0]
	v_pk_mul_f32 v[22:23], v[22:23], v[24:25] op_sel_hi:[1,0]
	v_pk_mul_f32 v[16:17], v[16:17], v[24:25] op_sel_hi:[1,0]
	v_pk_mul_f32 v[18:19], v[18:19], v[24:25] op_sel_hi:[1,0]
	s_waitcnt vmcnt(3)
	v_pk_mul_f32 v[26:27], v[38:39], v[26:27]
	v_pk_mul_f32 v[20:21], v[36:37], v[20:21]
	s_waitcnt vmcnt(2)
	v_pk_mul_f32 v[30:31], v[42:43], v[30:31]
	v_pk_mul_f32 v[34:35], v[40:41], v[34:35]
	s_waitcnt vmcnt(1)
	v_pk_mul_f32 v[18:19], v[46:47], v[18:19]
	v_pk_mul_f32 v[16:17], v[44:45], v[16:17]
	s_waitcnt vmcnt(0)
	v_pk_mul_f32 v[22:23], v[50:51], v[22:23]
	v_pk_mul_f32 v[28:29], v[48:49], v[28:29]
	s_and_b64 vcc, exec, s[10:11]
	s_cbranch_vccnz .LBB0_2498

;   DI void operator()(const f32x4 (&acc)[2][2][4][2], const pg8::Unit& u, int wr, int wc, int fr, int fq) const {
;     ...
;         if (type == T_NR) {
;           float s = 0.f;
; #pragma unroll
;           for (int n = 0; n < 2; ++n) s += v1[n].x * v1[n].x + v1[n].y * v1[n].y + v1[n].z * v1[n].z + v1[n].w * v1[n].w + v2[n].x * v2[n].x + v2[n].y * v2[n].y + v2[n].z * v2[n].z + v2[n].w * v2[n].w;
;           s += __shfl_xor(s, 16); s += __shfl_xor(s, 32);
;           const float rn = rsqrtf(s * (1.f / 64.f) + EPS);
; #pragma unroll
;           for (int n = 0; n < 2; ++n) { const f32x4 g1 = *(const f32x4*)(gain + n * 16 + fq * 4), g2 = *(const f32x4*)(gain + 32 + n * 16 + fq * 4); v1[n] = v1[n] * rn * g1; v2[n] = v2[n] * rn * g2; }
;         }
.LBB0_2519:
	global_load_dwordx4 v[20:23], v[146:147], off offset:64
	global_load_dwordx4 v[24:27], v[146:147], off
	global_load_dwordx4 v[28:31], v[146:147], off offset:192
	global_load_dwordx4 v[32:35], v[146:147], off offset:128
	v_mov_b32_e32 v36, v19
	v_mov_b32_e32 v37, v5
	v_mov_b32_e32 v8, v18
	v_mov_b32_e32 v9, v4
	v_pk_mul_f32 v[36:37], v[36:37], v[36:37]
	v_mov_b32_e32 v38, v14
	v_mov_b32_e32 v39, v10
	v_pk_fma_f32 v[8:9], v[8:9], v[8:9], v[36:37]
	v_mov_b32_e32 v40, v15
	v_mov_b32_e32 v41, v11
	v_pk_fma_f32 v[8:9], v[38:39], v[38:39], v[8:9]
	v_mov_b32_e32 v42, v12
	v_mov_b32_e32 v43, v0
	v_pk_fma_f32 v[8:9], v[40:41], v[40:41], v[8:9]
	v_mov_b32_e32 v44, v13
	v_mov_b32_e32 v45, v1
	v_and_b32_e32 v51, 64, v183
	v_pk_fma_f32 v[8:9], v[42:43], v[42:43], v[8:9]
	v_mov_b32_e32 v46, v6
	v_mov_b32_e32 v47, v2
	v_xor_b32_e32 v50, 16, v183
	v_add_u32_e32 v51, 64, v51
	v_pk_fma_f32 v[8:9], v[44:45], v[44:45], v[8:9]
	v_mov_b32_e32 v48, v7
	v_mov_b32_e32 v49, v3
	v_cmp_lt_i32_e32 vcc, v50, v51
	v_pk_fma_f32 v[8:9], v[46:47], v[46:47], v[8:9]
	s_nop 0
	v_cndmask_b32_e32 v36, v183, v50, vcc
	v_pk_fma_f32 v[8:9], v[48:49], v[48:49], v[8:9]
	v_lshlrev_b32_e32 v36, 2, v36
	v_add_f32_e32 v8, v8, v9
	ds_bpermute_b32 v9, v36, v8
	v_xor_b32_e32 v36, 32, v183
	v_cmp_lt_i32_e32 vcc, v36, v51
	s_waitcnt lgkmcnt(0)
	v_add_f32_e32 v8, v8, v9
	v_cndmask_b32_e32 v36, v183, v36, vcc
	v_lshlrev_b32_e32 v36, 2, v36
	v_mov_b32_e32 v9, v8
	s_nop 1
	v_permlane32_swap_b32_e32 v8, v9
	s_waitcnt lgkmcnt(0)
	v_add_f32_e32 v8, v8, v9
	v_fmamk_f32 v8, v8, 0x3c800000, v160
	v_mul_f32_e32 v9, 0x4b800000, v8
	v_cmp_gt_f32_e32 vcc, s59, v8
	s_nop 1
	v_cndmask_b32_e32 v8, v8, v9, vcc
	v_rsq_f32_e32 v8, v8
	s_nop 0
	v_mul_f32_e32 v9, 0x45800000, v8
	v_cndmask_b32_e32 v8, v8, v9, vcc
	v_pk_mul_f32 v[18:19], v[18:19], v[8:9] op_sel_hi:[1,0]
	v_pk_mul_f32 v[14:15], v[14:15], v[8:9] op_sel_hi:[1,0]
	v_pk_mul_f32 v[4:5], v[4:5], v[8:9] op_sel_hi:[1,0]
	v_pk_mul_f32 v[10:11], v[10:11], v[8:9] op_sel_hi:[1,0]
	v_pk_mul_f32 v[12:13], v[12:13], v[8:9] op_sel_hi:[1,0]
	v_pk_mul_f32 v[6:7], v[6:7], v[8:9] op_sel_hi:[1,0]
	v_pk_mul_f32 v[0:1], v[0:1], v[8:9] op_sel_hi:[1,0]
	v_pk_mul_f32 v[2:3], v[2:3], v[8:9] op_sel_hi:[1,0]
	s_waitcnt vmcnt(3)
	v_pk_mul_f32 v[10:11], v[22:23], v[10:11]
	v_pk_mul_f32 v[4:5], v[20:21], v[4:5]
	s_waitcnt vmcnt(2)
	v_pk_mul_f32 v[14:15], v[26:27], v[14:15]
	v_pk_mul_f32 v[18:19], v[24:25], v[18:19]
	s_waitcnt vmcnt(1)
	v_pk_mul_f32 v[2:3], v[30:31], v[2:3]
	v_pk_mul_f32 v[0:1], v[28:29], v[0:1]
	s_waitcnt vmcnt(0)
	v_pk_mul_f32 v[6:7], v[34:35], v[6:7]
	v_pk_mul_f32 v[12:13], v[32:33], v[12:13]
	s_and_b64 vcc, exec, s[10:11]
	s_cbranch_vccnz .LBB0_2502

; __device__ __forceinline__ unsigned xb_ld(unsigned* p)              { return __hip_atomic_load(p, __ATOMIC_RELAXED, __HIP_MEMORY_SCOPE_AGENT); }
; __device__ __forceinline__ unsigned xb_add(unsigned* p, unsigned v) { return __hip_atomic_fetch_add(p, v, __ATOMIC_RELAXED, __HIP_MEMORY_SCOPE_AGENT); }
; #define XB_SPIN(cond, bar) do { unsigned _sp = 0; while (cond) { __builtin_amdgcn_s_sleep(1); \
;     if ((++_sp & 255u) == 0u) { if (xb_ld(&(bar)[XB_TMO])) break; if (_sp > XB_SPIN_CAP) { atomicAdd(&(bar)[XB_TMO], 1u); break; } } } } while (0)
; __device__ __forceinline__ void xcd_barrier(const XcdBarrier& b) {
;     ...
;         const unsigned old = xb_add(&bar[XB_XSUB(b.x)], 1u);
;         const unsigned gen = old / nloc;
;         if (old + 1u == (gen + 1u) * nloc) {
;             __builtin_amdgcn_fence(__ATOMIC_RELEASE, "agent");
;             asm volatile("s_waitcnt vmcnt(0)" ::: "memory");
;             const unsigned og = xb_add(&bar[XB_TOP], 1u);
;             const unsigned tg = og / nx;
;             if (og + 1u == (tg + 1u) * nx) xb_add(&bar[XB_TOPGEN], 1u);
;             else XB_SPIN(xb_ld(&bar[XB_TOPGEN]) == tg, bar);
;             __builtin_amdgcn_fence(__ATOMIC_ACQUIRE, "agent");
;             xb_add(&bar[XB_XGEN(b.x)], 1u);
;             asm volatile("s_waitcnt vmcnt(0)" ::: "memory");
.LBB0_2573:
	s_or_b64 exec, exec, s[6:7]
	s_mov_b64 s[6:7], exec
	v_mbcnt_lo_u32_b32 v0, s6, 0
	v_mbcnt_hi_u32_b32 v0, s7, v0
	v_cmp_eq_u32_e32 vcc, 0, v0
	s_waitcnt vmcnt(0)
	buffer_inv sc1
	s_and_saveexec_b64 s[8:9], vcc
	s_cbranch_execz .LBB0_2575
	s_bcnt1_i32_b64 s6, s[6:7]
	v_mov_b32_e32 v0, 0x2000
	v_mov_b32_e32 v1, s6
	global_atomic_add v0, v1, s[2:3] offset:1024
	s_nop 0
	s_nop 0
	s_nop 0
	s_nop 0
	s_nop 0
	s_nop 0
	s_nop 0
	s_nop 0
	s_nop 0
	s_nop 0

; DI unsigned cvtpk(float lo, float hi) { f32x2_t v = {lo, hi}; bf16x2_t b = __builtin_convertvector(v, bf16x2_t); return __builtin_bit_cast(unsigned, b); }
;   DI void operator()(const f32x4 (&acc)[2][2][4][2], const pg8::Unit& u, int wr, int wc, int fr, int fq) const {
;     ...
;         const int row = u.pm * 256 + ai * 128 + wr * 64 + m * 16 + fr; float rs = 0.f;
; #pragma unroll
;         for (int bj = 0; bj < 2; ++bj)
; #pragma unroll
;           for (int n = 0; n < 2; ++n) {
;             const int col = u.pn * 256 + bj * 128 + wc * 32 + n * 16 + fq * 4; const size_t off = (size_t)row * DM + col;
;             f32x4 xb;
;             if (xin16) { const u32x2 hw = *(const u32x2*)(xin16 + off); xb.x = __uint_as_float(hw.x << 16); xb.y = __uint_as_float(hw.x & 0xffff0000u); xb.z = __uint_as_float(hw.y << 16); xb.w = __uint_as_float(hw.y & 0xffff0000u); }
;             else xb = *(const f32x4*)(xin + off);
;             const f32x4 xn = xb + acc[ai][bj][m][n];
;             { u32x2 wx; wx.x = cvtpk(xn.x, xn.y); wx.y = cvtpk(xn.z, xn.w); *(u32x2*)(X1B + off) = wx; }
;             rs += xn.x * xn.x + xn.y * xn.y + xn.z * xn.z + xn.w * xn.w;
;           }
;         rs += __shfl_xor(rs, 16); rs += __shfl_xor(rs, 32);
;         if (fq == 0) atomicAdd(ss + row, rs);
.LBB0_2712:
	v_lshl_add_u32 v142, s0, 8, v146
	v_lshl_or_b32 v140, s2, 8, v148
	v_ashrrev_i32_e32 v143, 31, v142
	v_lshlrev_b64 v[152:153], 10, v[142:143]
	v_ashrrev_i32_e32 v141, 31, v140
	v_lshl_add_u64 v[144:145], v[152:153], 0, v[140:141]
	v_lshlrev_b64 v[154:155], 1, v[144:145]
	v_lshl_add_u64 v[144:145], s[12:13], 0, v[154:155]
	global_load_dwordx2 v[156:157], v[144:145], off
	v_or_b32_e32 v144, 16, v140
	v_ashrrev_i32_e32 v145, 31, v144
	v_lshl_add_u64 v[158:159], v[152:153], 0, v[144:145]
	v_lshlrev_b64 v[158:159], 1, v[158:159]
	v_lshl_add_u64 v[154:155], s[14:15], 0, v[154:155]
	v_lshl_add_u64 v[160:161], s[12:13], 0, v[158:159]
	v_lshl_add_u64 v[158:159], s[14:15], 0, v[158:159]
	s_waitcnt vmcnt(0)
	v_lshlrev_b32_e32 v162, 16, v156
	v_and_b32_e32 v163, 0xffff0000, v156
	v_lshlrev_b32_e32 v156, 16, v157
	v_and_b32_e32 v157, 0xffff0000, v157
	v_pk_add_f32 v[126:127], v[126:127], v[156:157]
	v_pk_add_f32 v[156:157], v[124:125], v[162:163]
	v_cvt_pk_bf16_f32 v125, v126, v127
	v_cvt_pk_bf16_f32 v124, v156, v157
	global_store_dwordx2 v[154:155], v[124:125], off
	global_load_dwordx2 v[154:155], v[160:161], off
	v_or_b32_e32 v124, 0x80, v140
	v_ashrrev_i32_e32 v125, 31, v124
	v_lshl_add_u64 v[160:161], v[152:153], 0, v[124:125]
	v_lshlrev_b64 v[160:161], 1, v[160:161]
	v_lshl_add_u64 v[162:163], s[12:13], 0, v[160:161]
	v_lshl_add_u64 v[160:161], s[14:15], 0, v[160:161]
	v_mul_f32_e32 v157, v157, v157
	v_fmac_f32_e32 v157, v156, v156
	v_fmac_f32_e32 v157, v126, v126
	v_fmac_f32_e32 v157, v127, v127
	s_waitcnt vmcnt(0)
	v_lshlrev_b32_e32 v164, 16, v154
	v_and_b32_e32 v165, 0xffff0000, v154
	v_lshlrev_b32_e32 v154, 16, v155
	v_and_b32_e32 v155, 0xffff0000, v155
	v_pk_add_f32 v[122:123], v[122:123], v[154:155]
	v_pk_add_f32 v[154:155], v[120:121], v[164:165]
	v_cvt_pk_bf16_f32 v121, v122, v123
	v_cvt_pk_bf16_f32 v120, v154, v155
	global_store_dwordx2 v[158:159], v[120:121], off
	global_load_dwordx2 v[158:159], v[162:163], off
	v_or_b32_e32 v120, 0x90, v140
	v_ashrrev_i32_e32 v121, 31, v120
	v_lshl_add_u64 v[152:153], v[152:153], 0, v[120:121]
	v_lshlrev_b64 v[152:153], 1, v[152:153]
	v_lshl_add_u64 v[162:163], s[12:13], 0, v[152:153]
	v_mul_f32_e32 v126, v155, v155
	v_fmac_f32_e32 v126, v154, v154
	v_fmac_f32_e32 v126, v122, v122
	v_fmac_f32_e32 v126, v123, v123
	v_add_f32_e32 v122, v157, v126
	s_waitcnt vmcnt(0)
	v_lshlrev_b32_e32 v164, 16, v158
	v_and_b32_e32 v165, 0xffff0000, v158
	v_lshlrev_b32_e32 v158, 16, v159
	v_and_b32_e32 v159, 0xffff0000, v159
	v_pk_add_f32 v[118:119], v[118:119], v[158:159]
	v_pk_add_f32 v[158:159], v[116:117], v[164:165]
	v_cvt_pk_bf16_f32 v117, v118, v119
	v_cvt_pk_bf16_f32 v116, v158, v159
	global_store_dwordx2 v[160:161], v[116:117], off
	global_load_dwordx2 v[160:161], v[162:163], off
	v_mul_f32_e32 v123, v159, v159
	v_fmac_f32_e32 v123, v158, v158
	v_fmac_f32_e32 v123, v118, v118
	v_fmac_f32_e32 v123, v119, v119
	v_and_b32_e32 v117, 64, v183
	v_add_f32_e32 v126, v122, v123
	v_xor_b32_e32 v116, 16, v183
	v_add_u32_e32 v117, 64, v117
	v_cmp_lt_i32_e32 vcc, v116, v117
	s_waitcnt vmcnt(0)
	v_lshlrev_b32_e32 v118, 16, v160
	v_and_b32_e32 v119, 0xffff0000, v160
	v_pk_add_f32 v[118:119], v[112:113], v[118:119]
	v_lshlrev_b32_e32 v122, 16, v161
	v_and_b32_e32 v123, 0xffff0000, v161
	v_mul_f32_e32 v112, v119, v119
	v_pk_add_f32 v[122:123], v[114:115], v[122:123]
	v_fmac_f32_e32 v112, v118, v118
	v_fmac_f32_e32 v112, v122, v122
	v_cndmask_b32_e32 v116, v183, v116, vcc
	v_fmac_f32_e32 v112, v123, v123
	v_lshlrev_b32_e32 v116, 2, v116
	v_add_f32_e32 v112, v126, v112
	v_mov_b32_e32 v113, v112
	s_nop 1
	v_permlane16_swap_b32_e32 v112, v113
	v_xor_b32_e32 v114, 32, v183
	v_cmp_lt_i32_e32 vcc, v114, v117
	v_cvt_pk_bf16_f32 v118, v118, v119
	v_cvt_pk_bf16_f32 v119, v122, v123
	v_cndmask_b32_e32 v114, v183, v114, vcc
	v_lshlrev_b32_e32 v114, 2, v114
	s_waitcnt lgkmcnt(0)
	v_add_f32_e32 v112, v112, v113
	ds_bpermute_b32 v113, v114, v112
	v_lshl_add_u64 v[122:123], s[14:15], 0, v[152:153]
	global_store_dwordx2 v[122:123], v[118:119], off
	s_and_saveexec_b64 s[0:1], s[6:7]
	s_cbranch_execz .LBB0_2714
	s_waitcnt lgkmcnt(0)
	v_add_f32_e32 v115, v112, v113
	v_lshl_add_u64 v[112:113], v[142:143], 2, s[16:17]
	global_atomic_add_f32 v[112:113], v115, off
